# grid-barrier leader releases XCD waiters before its own L2 invalidate; GU epilogue next-stat reduction shuffles batched
# speedup vs baseline: 1.0132x; 1.0005x over previous
; DI unsigned xb_add(unsigned* p, unsigned v) { return __hip_atomic_fetch_add(p, v, __ATOMIC_RELAXED, __HIP_MEMORY_SCOPE_AGENT); }
; DI void xcd_barrier(int wv, unsigned* bar, volatile LAS unsigned* st) {
;     ...
;             __builtin_amdgcn_fence(__ATOMIC_ACQUIRE, "agent");
;             xb_add(&bar[XB_XGEN(x)], 1u);
;             asm volatile("s_waitcnt vmcnt(0)" ::: "memory");
.LBB0_1796:
	s_or_b64 exec, exec, s[0:1]
	v_mov_b32_e32 v0, s25
	v_add_co_u32_e32 v0, vcc, 0x2000, v0
	v_mov_b32_e32 v1, s24
	s_nop 0
	v_addc_co_u32_e32 v1, vcc, 0, v1, vcc
	v_mov_b32_e32 v2, 1
	s_waitcnt vmcnt(0) lgkmcnt(0)
	flat_atomic_add v[0:1], v2 offset:1024
	buffer_inv sc1
	s_waitcnt vmcnt(0)

; DI unsigned xb_add(unsigned* p, unsigned v) { return __hip_atomic_fetch_add(p, v, __ATOMIC_RELAXED, __HIP_MEMORY_SCOPE_AGENT); }
; DI void xcd_barrier(int wv, unsigned* bar, volatile LAS unsigned* st) {
;     ...
;             __builtin_amdgcn_fence(__ATOMIC_ACQUIRE, "agent");
;             xb_add(&bar[XB_XGEN(x)], 1u);
;             asm volatile("s_waitcnt vmcnt(0)" ::: "memory");
.LBB0_1801:
	s_or_b64 exec, exec, s[0:1]
	v_mov_b32_e32 v0, s25
	v_add_co_u32_e32 v2, vcc, 0x2000, v0
	v_mov_b32_e32 v0, s24
	s_nop 0
	v_addc_co_u32_e32 v3, vcc, 0, v0, vcc
	v_mov_b32_e32 v0, 1
	s_waitcnt vmcnt(0) lgkmcnt(0)
	flat_atomic_add v[2:3], v0 offset:1024
	buffer_inv sc1
	s_waitcnt vmcnt(0)

; DI u32x4 pk8(f32x4 a, f32x4 b) { u32x4 o; o.x = pk2(a.x, a.y); o.y = pk2(a.z, a.w); o.z = pk2(b.x, b.y); o.w = pk2(b.z, b.w); return o; }
; DI float fexp2(float x) { return __builtin_amdgcn_exp2f(x); }
; DI float frcp(float x) { return __builtin_amdgcn_rcpf(x); }
; #define EPI_SCHED() __builtin_amdgcn_sched_barrier(0)
;     DI void operator()(const AccT& acc, const Unit& u, const Unit& nxt, bool has_next, int wr, int wc, int fr, int fq, float (&rs_unused)[2][4]) const {
;     ...
; #pragma unroll
;         for (int ai = 0; ai < 2; ++ai)
; #pragma unroll
;             for (int m = 0; m < 4; ++m) {
;                 EPI_SCHED(); const size_t row = row0 + ai * 128 + m * 16;
;                 f32x4 o[2];
;                 const float c1 = -LOG2E * rs[ai][m], rs2 = rs[ai][m] * rs[ai][m];
; #pragma unroll
;                 for (int n = 0; n < 2; ++n) {
;                     const f32x4 gt = acc[ai][0][m][n], t = gt * acc[ai][1][m][n];
; #pragma unroll
;                     for (int e = 0; e < 4; ++e) o[n][e] = t[e] * (rs2 * frcp(1.f + fexp2(gt[e] * c1)));
;                 }
;                 *(u32x4*)(hid + row * FF + u.pn * 128 + wc * 32 + fq * 8) = pk8(o[0], o[1]);
.LBB0_1822:
	s_ashr_i32 s23, s22, 31
	s_lshl_b64 s[22:23], s[22:23], 8
	s_add_u32 s1, s22, s39
	s_addc_u32 s15, s23, s44
	s_lshl_b32 s22, s0, 7
	v_lshlrev_b32_e32 v178, 3, v178
	v_or_b32_e32 v188, s1, v179
	s_ashr_i32 s23, s22, 31
	v_ashrrev_i32_e32 v179, 31, v178
	s_waitcnt lgkmcnt(0)
	v_mul_f32_e32 v185, 0xbfb8aa3b, v150
	v_mul_f32_e32 v180, v134, v185
	v_mul_f32_e32 v181, v135, v185
	v_exp_f32_e32 v180, v180
	v_exp_f32_e32 v181, v181
	v_mul_f32_e32 v182, v136, v185
	v_mul_f32_e32 v183, v137, v185
	v_exp_f32_e32 v182, v182
	v_exp_f32_e32 v183, v183
	v_mul_f32_e32 v184, v130, v185
	v_mul_f32_e32 v186, v131, v185
	v_exp_f32_e32 v184, v184
	v_exp_f32_e32 v186, v186
	v_add_f32_e32 v180, 1.0, v180
	v_add_f32_e32 v181, 1.0, v181
	v_mul_f32_e32 v187, v132, v185
	v_mul_f32_e32 v185, v133, v185
	v_rcp_f32_e32 v180, v180
	v_rcp_f32_e32 v181, v181
	v_add_f32_e32 v182, 1.0, v182
	v_add_f32_e32 v183, 1.0, v183
	v_exp_f32_e32 v187, v187
	v_exp_f32_e32 v189, v185
	v_rcp_f32_e32 v182, v182
	v_rcp_f32_e32 v183, v183
	v_add_f32_e32 v184, 1.0, v184
	v_add_f32_e32 v186, 1.0, v186
	v_mul_f32_e32 v150, v150, v150
	v_rcp_f32_e32 v184, v184
	v_rcp_f32_e32 v185, v186
	v_add_f32_e32 v186, 1.0, v187
	v_add_f32_e32 v187, 1.0, v189
	v_pk_mul_f32 v[126:127], v[134:135], v[126:127]
	v_pk_mul_f32 v[134:135], v[150:151], v[180:181] op_sel_hi:[0,1]
	v_rcp_f32_e32 v186, v186
	v_rcp_f32_e32 v187, v187
	v_pk_mul_f32 v[128:129], v[136:137], v[128:129]
	v_pk_mul_f32 v[126:127], v[126:127], v[134:135]
	v_pk_mul_f32 v[134:135], v[150:151], v[182:183] op_sel_hi:[0,1]
	v_pk_mul_f32 v[128:129], v[128:129], v[134:135]
	v_cvt_pk_bf16_f32 v126, v126, v127
	v_cvt_pk_bf16_f32 v127, v128, v129
	v_pk_mul_f32 v[122:123], v[130:131], v[122:123]
	v_pk_mul_f32 v[128:129], v[150:151], v[184:185] op_sel_hi:[0,1]
	v_pk_mul_f32 v[122:123], v[122:123], v[128:129]
	v_pk_mul_f32 v[124:125], v[132:133], v[124:125]
	v_cvt_pk_bf16_f32 v128, v122, v123
	v_pk_mul_f32 v[122:123], v[150:151], v[186:187] op_sel_hi:[0,1]
	v_pk_mul_f32 v[122:123], v[124:125], v[122:123]
	s_movk_i32 s0, 0x1600
	v_cvt_pk_bf16_f32 v129, v122, v123
	v_mov_b64_e32 v[122:123], s[8:9]
	v_mad_u64_u32 v[122:123], s[0:1], v188, s0, v[122:123]
	v_mov_b32_e32 v124, 0x1600
	v_mad_i32_i24 v123, s15, v124, v123
	v_lshl_add_u64 v[122:123], s[22:23], 1, v[122:123]
	v_lshl_add_u64 v[122:123], v[122:123], 0, s[96:97]
	v_lshl_add_u64 v[122:123], v[178:179], 1, v[122:123]
	flat_store_dwordx4 v[122:123], v[126:129]
	v_mul_f32_e32 v125, 0xbfb8aa3b, v151
	v_mul_f32_e32 v124, v114, v125
	v_exp_f32_e32 v126, v124
	v_mul_f32_e32 v124, v115, v125
	v_exp_f32_e32 v127, v124
	v_mul_f32_e32 v128, v116, v125
	v_mul_f32_e32 v129, v117, v125
	v_exp_f32_e32 v128, v128
	v_exp_f32_e32 v129, v129
	v_mul_f32_e32 v130, v110, v125
	v_mul_f32_e32 v131, v111, v125
	v_exp_f32_e32 v130, v130
	v_exp_f32_e32 v131, v131
	v_mul_f32_e32 v132, v112, v125
	v_mul_f32_e32 v125, v113, v125
	v_add_f32_e32 v126, 1.0, v126
	v_add_f32_e32 v127, 1.0, v127
	v_exp_f32_e32 v125, v125
	v_rcp_f32_e32 v126, v126
	v_rcp_f32_e32 v127, v127
	v_add_f32_e32 v128, 1.0, v128
	v_add_f32_e32 v129, 1.0, v129
	v_exp_f32_e32 v132, v132
	v_rcp_f32_e32 v128, v128
	v_rcp_f32_e32 v129, v129
	v_add_f32_e32 v130, 1.0, v130
	v_add_f32_e32 v131, 1.0, v131
	v_mul_f32_e32 v124, v151, v151
	v_rcp_f32_e32 v130, v130
	v_rcp_f32_e32 v131, v131
	v_add_f32_e32 v125, 1.0, v125
	v_add_f32_e32 v132, 1.0, v132
	v_pk_mul_f32 v[106:107], v[114:115], v[106:107]
	v_pk_mul_f32 v[114:115], v[124:125], v[126:127] op_sel_hi:[0,1]
	v_rcp_f32_e32 v132, v132
	v_rcp_f32_e32 v133, v125
	v_pk_mul_f32 v[108:109], v[116:117], v[108:109]
	v_pk_mul_f32 v[106:107], v[106:107], v[114:115]
	v_pk_mul_f32 v[114:115], v[124:125], v[128:129] op_sel_hi:[0,1]
	v_pk_mul_f32 v[108:109], v[108:109], v[114:115]
	v_cvt_pk_bf16_f32 v106, v106, v107
	v_cvt_pk_bf16_f32 v107, v108, v109
	v_pk_mul_f32 v[102:103], v[110:111], v[102:103]
	v_pk_mul_f32 v[108:109], v[124:125], v[130:131] op_sel_hi:[0,1]
	v_pk_mul_f32 v[102:103], v[102:103], v[108:109]
	v_pk_mul_f32 v[104:105], v[112:113], v[104:105]
	v_cvt_pk_bf16_f32 v108, v102, v103
	v_pk_mul_f32 v[102:103], v[124:125], v[132:133] op_sel_hi:[0,1]
	v_pk_mul_f32 v[102:103], v[104:105], v[102:103]
	s_mov_b32 s0, 0x16000
	v_cvt_pk_bf16_f32 v109, v102, v103
	v_add_co_u32_e32 v102, vcc, s0, v122
	s_nop 1
	v_addc_co_u32_e32 v103, vcc, 0, v123, vcc
	flat_store_dwordx4 v[102:103], v[106:109]
	v_mul_f32_e32 v103, 0xbfb8aa3b, v152
	v_mul_f32_e32 v102, v94, v103
	v_exp_f32_e32 v104, v102
	v_mul_f32_e32 v102, v95, v103
	v_exp_f32_e32 v105, v102
	v_mul_f32_e32 v106, v96, v103
	v_mul_f32_e32 v107, v97, v103
	v_exp_f32_e32 v106, v106
	v_exp_f32_e32 v107, v107
	v_mul_f32_e32 v108, v90, v103
	v_mul_f32_e32 v109, v91, v103
	v_exp_f32_e32 v108, v108
	v_exp_f32_e32 v109, v109
	v_mul_f32_e32 v110, v92, v103
	v_mul_f32_e32 v103, v93, v103
	v_add_f32_e32 v104, 1.0, v104
	v_add_f32_e32 v105, 1.0, v105
	v_exp_f32_e32 v103, v103
	v_rcp_f32_e32 v104, v104
	v_rcp_f32_e32 v105, v105
	v_add_f32_e32 v106, 1.0, v106
	v_add_f32_e32 v107, 1.0, v107
	v_exp_f32_e32 v110, v110
	v_rcp_f32_e32 v106, v106
	v_rcp_f32_e32 v107, v107
	v_add_f32_e32 v108, 1.0, v108
	v_add_f32_e32 v109, 1.0, v109
	v_mul_f32_e32 v102, v152, v152
	v_rcp_f32_e32 v108, v108
	v_rcp_f32_e32 v109, v109
	v_add_f32_e32 v103, 1.0, v103
	v_add_f32_e32 v110, 1.0, v110
	v_pk_mul_f32 v[86:87], v[94:95], v[86:87]
	v_pk_mul_f32 v[94:95], v[102:103], v[104:105] op_sel_hi:[0,1]
	v_rcp_f32_e32 v110, v110
	v_rcp_f32_e32 v111, v103
	v_pk_mul_f32 v[88:89], v[96:97], v[88:89]
	v_pk_mul_f32 v[86:87], v[86:87], v[94:95]
	v_pk_mul_f32 v[94:95], v[102:103], v[106:107] op_sel_hi:[0,1]
; DI u32x4 pk8(f32x4 a, f32x4 b) { u32x4 o; o.x = pk2(a.x, a.y); o.y = pk2(a.z, a.w); o.z = pk2(b.x, b.y); o.w = pk2(b.z, b.w); return o; }
; DI float fexp2(float x) { return __builtin_amdgcn_exp2f(x); }
; DI float frcp(float x) { return __builtin_amdgcn_rcpf(x); }
; #define EPI_SCHED() __builtin_amdgcn_sched_barrier(0)
;     DI void operator()(const AccT& acc, const Unit& u, const Unit& nxt, bool has_next, int wr, int wc, int fr, int fq, float (&rs_unused)[2][4]) const {
;     ...
; #pragma unroll
;         for (int ai = 0; ai < 2; ++ai)
; #pragma unroll
;             for (int m = 0; m < 4; ++m) {
;                 EPI_SCHED(); const size_t row = row0 + ai * 128 + m * 16;
;                 f32x4 o[2];
;                 const float c1 = -LOG2E * rs[ai][m], rs2 = rs[ai][m] * rs[ai][m];
; #pragma unroll
;                 for (int n = 0; n < 2; ++n) {
;                     const f32x4 gt = acc[ai][0][m][n], t = gt * acc[ai][1][m][n];
; #pragma unroll
;                     for (int e = 0; e < 4; ++e) o[n][e] = t[e] * (rs2 * frcp(1.f + fexp2(gt[e] * c1)));
;                 }
;                 *(u32x4*)(hid + row * FF + u.pn * 128 + wc * 32 + fq * 8) = pk8(o[0], o[1]);
	v_pk_mul_f32 v[88:89], v[88:89], v[94:95]
	v_cvt_pk_bf16_f32 v86, v86, v87
	v_cvt_pk_bf16_f32 v87, v88, v89
	v_pk_mul_f32 v[82:83], v[90:91], v[82:83]
	v_pk_mul_f32 v[88:89], v[102:103], v[108:109] op_sel_hi:[0,1]
	v_pk_mul_f32 v[82:83], v[82:83], v[88:89]
	v_pk_mul_f32 v[84:85], v[92:93], v[84:85]
	v_cvt_pk_bf16_f32 v88, v82, v83
	v_pk_mul_f32 v[82:83], v[102:103], v[110:111] op_sel_hi:[0,1]
	v_pk_mul_f32 v[82:83], v[84:85], v[82:83]
	s_mov_b32 s0, 0x2c000
	v_cvt_pk_bf16_f32 v89, v82, v83
	v_add_co_u32_e32 v82, vcc, s0, v122
	s_nop 1
	v_addc_co_u32_e32 v83, vcc, 0, v123, vcc
	flat_store_dwordx4 v[82:83], v[86:89]
	v_mul_f32_e32 v83, 0xbfb8aa3b, v153
	v_mul_f32_e32 v82, v78, v83
	v_exp_f32_e32 v84, v82
	v_mul_f32_e32 v82, v79, v83
	v_exp_f32_e32 v85, v82
	v_mul_f32_e32 v86, v80, v83
	v_mul_f32_e32 v87, v81, v83
	v_exp_f32_e32 v86, v86
	v_exp_f32_e32 v87, v87
	v_mul_f32_e32 v88, v74, v83
	v_mul_f32_e32 v89, v75, v83
	v_exp_f32_e32 v88, v88
	v_exp_f32_e32 v89, v89
	v_mul_f32_e32 v90, v76, v83
	v_mul_f32_e32 v83, v77, v83
	v_add_f32_e32 v84, 1.0, v84
	v_add_f32_e32 v85, 1.0, v85
	v_exp_f32_e32 v83, v83
	v_rcp_f32_e32 v84, v84
	v_rcp_f32_e32 v85, v85
	v_add_f32_e32 v86, 1.0, v86
	v_add_f32_e32 v87, 1.0, v87
	v_exp_f32_e32 v90, v90
	v_rcp_f32_e32 v86, v86
	v_rcp_f32_e32 v87, v87
	v_add_f32_e32 v88, 1.0, v88
	v_add_f32_e32 v89, 1.0, v89
	v_mul_f32_e32 v82, v153, v153
	v_rcp_f32_e32 v88, v88
	v_rcp_f32_e32 v89, v89
	v_add_f32_e32 v83, 1.0, v83
	v_add_f32_e32 v90, 1.0, v90
	v_pk_mul_f32 v[70:71], v[78:79], v[70:71]
	v_pk_mul_f32 v[78:79], v[82:83], v[84:85] op_sel_hi:[0,1]
	v_rcp_f32_e32 v90, v90
	v_rcp_f32_e32 v91, v83
	v_pk_mul_f32 v[72:73], v[80:81], v[72:73]
	v_pk_mul_f32 v[70:71], v[70:71], v[78:79]
	v_pk_mul_f32 v[78:79], v[82:83], v[86:87] op_sel_hi:[0,1]
	v_pk_mul_f32 v[72:73], v[72:73], v[78:79]
	v_cvt_pk_bf16_f32 v70, v70, v71
	v_cvt_pk_bf16_f32 v71, v72, v73
	v_pk_mul_f32 v[66:67], v[74:75], v[66:67]
	v_pk_mul_f32 v[72:73], v[82:83], v[88:89] op_sel_hi:[0,1]
	v_pk_mul_f32 v[66:67], v[66:67], v[72:73]
	v_pk_mul_f32 v[68:69], v[76:77], v[68:69]
	v_cvt_pk_bf16_f32 v72, v66, v67
	v_pk_mul_f32 v[66:67], v[82:83], v[90:91] op_sel_hi:[0,1]
	v_pk_mul_f32 v[66:67], v[68:69], v[66:67]
	s_mov_b32 s0, 0x42000
	v_cvt_pk_bf16_f32 v73, v66, v67
	v_add_co_u32_e32 v66, vcc, s0, v122
	s_nop 1
	v_addc_co_u32_e32 v67, vcc, 0, v123, vcc
	flat_store_dwordx4 v[66:67], v[70:73]
	v_mul_f32_e32 v67, 0xbfb8aa3b, v146
	v_mul_f32_e32 v66, v62, v67
	v_exp_f32_e32 v68, v66
	v_mul_f32_e32 v66, v63, v67
	v_exp_f32_e32 v69, v66
	v_mul_f32_e32 v70, v64, v67
	v_mul_f32_e32 v71, v65, v67
	v_exp_f32_e32 v70, v70
	v_exp_f32_e32 v71, v71
	v_mul_f32_e32 v72, v58, v67
	v_mul_f32_e32 v73, v59, v67
	v_exp_f32_e32 v72, v72
	v_exp_f32_e32 v73, v73
	v_mul_f32_e32 v74, v60, v67
	v_mul_f32_e32 v67, v61, v67
	v_add_f32_e32 v68, 1.0, v68
	v_add_f32_e32 v69, 1.0, v69
	v_exp_f32_e32 v67, v67
	v_rcp_f32_e32 v68, v68
	v_rcp_f32_e32 v69, v69
	v_add_f32_e32 v70, 1.0, v70
	v_add_f32_e32 v71, 1.0, v71
	v_exp_f32_e32 v74, v74
	v_rcp_f32_e32 v70, v70
	v_rcp_f32_e32 v71, v71
	v_add_f32_e32 v72, 1.0, v72
	v_add_f32_e32 v73, 1.0, v73
	v_mul_f32_e32 v66, v146, v146
	v_rcp_f32_e32 v72, v72
	v_rcp_f32_e32 v73, v73
	v_add_f32_e32 v67, 1.0, v67
	v_add_f32_e32 v74, 1.0, v74
	v_pk_mul_f32 v[54:55], v[62:63], v[54:55]
	v_pk_mul_f32 v[62:63], v[66:67], v[68:69] op_sel_hi:[0,1]
	v_rcp_f32_e32 v74, v74
	v_rcp_f32_e32 v75, v67
	v_pk_mul_f32 v[56:57], v[64:65], v[56:57]
	v_pk_mul_f32 v[54:55], v[54:55], v[62:63]
	v_pk_mul_f32 v[62:63], v[66:67], v[70:71] op_sel_hi:[0,1]
	v_pk_mul_f32 v[56:57], v[56:57], v[62:63]
	v_cvt_pk_bf16_f32 v54, v54, v55
	v_cvt_pk_bf16_f32 v55, v56, v57
	v_pk_mul_f32 v[50:51], v[58:59], v[50:51]
	v_pk_mul_f32 v[56:57], v[66:67], v[72:73] op_sel_hi:[0,1]
	v_pk_mul_f32 v[50:51], v[50:51], v[56:57]
	v_pk_mul_f32 v[52:53], v[60:61], v[52:53]
	v_cvt_pk_bf16_f32 v56, v50, v51
	v_pk_mul_f32 v[50:51], v[66:67], v[74:75] op_sel_hi:[0,1]
	v_pk_mul_f32 v[50:51], v[52:53], v[50:51]
	s_mov_b32 s0, 0xb0000
	v_cvt_pk_bf16_f32 v57, v50, v51
	v_add_co_u32_e32 v50, vcc, s0, v122
	s_nop 1
	v_addc_co_u32_e32 v51, vcc, 0, v123, vcc
	flat_store_dwordx4 v[50:51], v[54:57]
	v_mul_f32_e32 v51, 0xbfb8aa3b, v147
	v_mul_f32_e32 v50, v46, v51
	v_exp_f32_e32 v52, v50
	v_mul_f32_e32 v50, v47, v51
	v_exp_f32_e32 v53, v50
	v_mul_f32_e32 v54, v48, v51
	v_mul_f32_e32 v55, v49, v51
	v_exp_f32_e32 v54, v54
	v_exp_f32_e32 v55, v55
	v_mul_f32_e32 v56, v42, v51
	v_mul_f32_e32 v57, v43, v51
	v_exp_f32_e32 v56, v56
	v_exp_f32_e32 v57, v57
	v_mul_f32_e32 v58, v44, v51
	v_mul_f32_e32 v51, v45, v51
	v_add_f32_e32 v52, 1.0, v52
	v_add_f32_e32 v53, 1.0, v53
	v_exp_f32_e32 v51, v51
	v_rcp_f32_e32 v52, v52
	v_rcp_f32_e32 v53, v53
	v_add_f32_e32 v54, 1.0, v54
	v_add_f32_e32 v55, 1.0, v55
	v_exp_f32_e32 v58, v58
	v_rcp_f32_e32 v54, v54
	v_rcp_f32_e32 v55, v55
	v_add_f32_e32 v56, 1.0, v56
	v_add_f32_e32 v57, 1.0, v57
	v_mul_f32_e32 v50, v147, v147
	v_rcp_f32_e32 v56, v56
	v_rcp_f32_e32 v57, v57
	v_add_f32_e32 v51, 1.0, v51
	v_add_f32_e32 v58, 1.0, v58
	v_pk_mul_f32 v[38:39], v[46:47], v[38:39]
	v_pk_mul_f32 v[46:47], v[50:51], v[52:53] op_sel_hi:[0,1]
	v_rcp_f32_e32 v58, v58
	v_rcp_f32_e32 v59, v51
	v_pk_mul_f32 v[40:41], v[48:49], v[40:41]
	v_pk_mul_f32 v[38:39], v[38:39], v[46:47]
	v_pk_mul_f32 v[46:47], v[50:51], v[54:55] op_sel_hi:[0,1]
	v_pk_mul_f32 v[40:41], v[40:41], v[46:47]
	v_cvt_pk_bf16_f32 v38, v38, v39
	v_cvt_pk_bf16_f32 v39, v40, v41
	v_pk_mul_f32 v[34:35], v[42:43], v[34:35]
	v_pk_mul_f32 v[40:41], v[50:51], v[56:57] op_sel_hi:[0,1]
	v_pk_mul_f32 v[34:35], v[34:35], v[40:41]
	v_pk_mul_f32 v[36:37], v[44:45], v[36:37]
; DI u32x4 pk8(f32x4 a, f32x4 b) { u32x4 o; o.x = pk2(a.x, a.y); o.y = pk2(a.z, a.w); o.z = pk2(b.x, b.y); o.w = pk2(b.z, b.w); return o; }
; DI float fexp2(float x) { return __builtin_amdgcn_exp2f(x); }
; DI float frcp(float x) { return __builtin_amdgcn_rcpf(x); }
; #define EPI_SCHED() __builtin_amdgcn_sched_barrier(0)
;     DI void operator()(const AccT& acc, const Unit& u, const Unit& nxt, bool has_next, int wr, int wc, int fr, int fq, float (&rs_unused)[2][4]) const {
;     ...
; #pragma unroll
;         for (int ai = 0; ai < 2; ++ai)
; #pragma unroll
;             for (int m = 0; m < 4; ++m) {
;                 EPI_SCHED(); const size_t row = row0 + ai * 128 + m * 16;
;                 f32x4 o[2];
;                 const float c1 = -LOG2E * rs[ai][m], rs2 = rs[ai][m] * rs[ai][m];
; #pragma unroll
;                 for (int n = 0; n < 2; ++n) {
;                     const f32x4 gt = acc[ai][0][m][n], t = gt * acc[ai][1][m][n];
; #pragma unroll
;                     for (int e = 0; e < 4; ++e) o[n][e] = t[e] * (rs2 * frcp(1.f + fexp2(gt[e] * c1)));
;                 }
;                 *(u32x4*)(hid + row * FF + u.pn * 128 + wc * 32 + fq * 8) = pk8(o[0], o[1]);
	v_cvt_pk_bf16_f32 v40, v34, v35
	v_pk_mul_f32 v[34:35], v[50:51], v[58:59] op_sel_hi:[0,1]
	v_pk_mul_f32 v[34:35], v[36:37], v[34:35]
	s_mov_b32 s0, 0xc6000
	v_cvt_pk_bf16_f32 v41, v34, v35
	v_add_co_u32_e32 v34, vcc, s0, v122
	s_nop 1
	v_addc_co_u32_e32 v35, vcc, 0, v123, vcc
	flat_store_dwordx4 v[34:35], v[38:41]
	v_mul_f32_e32 v35, 0xbfb8aa3b, v148
	v_mul_f32_e32 v34, v30, v35
	v_exp_f32_e32 v36, v34
	v_mul_f32_e32 v34, v31, v35
	v_exp_f32_e32 v37, v34
	v_mul_f32_e32 v38, v32, v35
	v_mul_f32_e32 v39, v33, v35
	v_exp_f32_e32 v38, v38
	v_exp_f32_e32 v39, v39
	v_mul_f32_e32 v40, v26, v35
	v_mul_f32_e32 v41, v27, v35
	v_exp_f32_e32 v40, v40
	v_exp_f32_e32 v41, v41
	v_mul_f32_e32 v42, v28, v35
	v_mul_f32_e32 v35, v29, v35
	v_add_f32_e32 v36, 1.0, v36
	v_add_f32_e32 v37, 1.0, v37
	v_exp_f32_e32 v35, v35
	v_rcp_f32_e32 v36, v36
	v_rcp_f32_e32 v37, v37
	v_add_f32_e32 v38, 1.0, v38
	v_add_f32_e32 v39, 1.0, v39
	v_exp_f32_e32 v42, v42
	v_rcp_f32_e32 v38, v38
	v_rcp_f32_e32 v39, v39
	v_add_f32_e32 v40, 1.0, v40
	v_add_f32_e32 v41, 1.0, v41
	v_mul_f32_e32 v34, v148, v148
	v_rcp_f32_e32 v40, v40
	v_rcp_f32_e32 v41, v41
	v_add_f32_e32 v35, 1.0, v35
	v_add_f32_e32 v42, 1.0, v42
	v_pk_mul_f32 v[22:23], v[30:31], v[22:23]
	v_pk_mul_f32 v[30:31], v[34:35], v[36:37] op_sel_hi:[0,1]
	v_rcp_f32_e32 v42, v42
	v_rcp_f32_e32 v43, v35
	v_pk_mul_f32 v[24:25], v[32:33], v[24:25]
	v_pk_mul_f32 v[22:23], v[22:23], v[30:31]
	v_pk_mul_f32 v[30:31], v[34:35], v[38:39] op_sel_hi:[0,1]
	v_pk_mul_f32 v[24:25], v[24:25], v[30:31]
	v_cvt_pk_bf16_f32 v22, v22, v23
	v_cvt_pk_bf16_f32 v23, v24, v25
	v_pk_mul_f32 v[18:19], v[26:27], v[18:19]
	v_pk_mul_f32 v[24:25], v[34:35], v[40:41] op_sel_hi:[0,1]
	v_pk_mul_f32 v[18:19], v[18:19], v[24:25]
	v_pk_mul_f32 v[20:21], v[28:29], v[20:21]
	v_cvt_pk_bf16_f32 v24, v18, v19
	v_pk_mul_f32 v[18:19], v[34:35], v[42:43] op_sel_hi:[0,1]
	v_pk_mul_f32 v[18:19], v[20:21], v[18:19]
	s_mov_b32 s0, 0xdc000
	v_cvt_pk_bf16_f32 v25, v18, v19
	v_add_co_u32_e32 v18, vcc, s0, v122
	s_nop 1
	v_addc_co_u32_e32 v19, vcc, 0, v123, vcc
	flat_store_dwordx4 v[18:19], v[22:25]
	v_mul_f32_e32 v19, 0xbfb8aa3b, v149
	v_mul_f32_e32 v18, v14, v19
	v_exp_f32_e32 v20, v18
	v_mul_f32_e32 v18, v15, v19
	v_exp_f32_e32 v21, v18
	v_mul_f32_e32 v22, v16, v19
	v_mul_f32_e32 v23, v17, v19
	v_exp_f32_e32 v22, v22
	v_exp_f32_e32 v23, v23
	v_mul_f32_e32 v24, v10, v19
	v_mul_f32_e32 v25, v11, v19
	v_exp_f32_e32 v24, v24
	v_exp_f32_e32 v25, v25
	v_mul_f32_e32 v26, v12, v19
	v_mul_f32_e32 v19, v13, v19
	v_add_f32_e32 v20, 1.0, v20
	v_add_f32_e32 v21, 1.0, v21
	v_exp_f32_e32 v19, v19
	v_rcp_f32_e32 v20, v20
	v_rcp_f32_e32 v21, v21
	v_add_f32_e32 v22, 1.0, v22
	v_add_f32_e32 v23, 1.0, v23
	v_exp_f32_e32 v26, v26
	v_rcp_f32_e32 v22, v22
	v_rcp_f32_e32 v23, v23
	v_add_f32_e32 v24, 1.0, v24
	v_add_f32_e32 v25, 1.0, v25
	v_mul_f32_e32 v18, v149, v149
	v_rcp_f32_e32 v24, v24
	v_rcp_f32_e32 v25, v25
	v_add_f32_e32 v19, 1.0, v19
	v_add_f32_e32 v26, 1.0, v26
	v_pk_mul_f32 v[6:7], v[14:15], v[6:7]
	v_pk_mul_f32 v[14:15], v[18:19], v[20:21] op_sel_hi:[0,1]
	v_rcp_f32_e32 v26, v26
	v_rcp_f32_e32 v27, v19
	v_pk_mul_f32 v[8:9], v[16:17], v[8:9]
	v_pk_mul_f32 v[6:7], v[6:7], v[14:15]
	v_pk_mul_f32 v[14:15], v[18:19], v[22:23] op_sel_hi:[0,1]
	v_pk_mul_f32 v[8:9], v[8:9], v[14:15]
	v_cvt_pk_bf16_f32 v6, v6, v7
	v_cvt_pk_bf16_f32 v7, v8, v9
	v_pk_mul_f32 v[2:3], v[10:11], v[2:3]
	v_pk_mul_f32 v[8:9], v[18:19], v[24:25] op_sel_hi:[0,1]
	v_pk_mul_f32 v[2:3], v[2:3], v[8:9]
	v_pk_mul_f32 v[4:5], v[12:13], v[4:5]
	v_cvt_pk_bf16_f32 v8, v2, v3
	v_pk_mul_f32 v[2:3], v[18:19], v[26:27] op_sel_hi:[0,1]
	v_pk_mul_f32 v[2:3], v[4:5], v[2:3]
	s_nop 0
	v_cvt_pk_bf16_f32 v9, v2, v3
	v_add_co_u32_e32 v2, vcc, 0xf2000, v122
	s_nop 1
	v_addc_co_u32_e32 v3, vcc, 0, v123, vcc
	s_and_b64 vcc, exec, s[2:3]
	s_mov_b64 s[2:3], -1
	flat_store_dwordx4 v[2:3], v[6:9]
	s_cbranch_vccnz .LBB0_1813
;     DI static void park(const float (&rs)[2][4], int t) { LAS f32x4* p = slot(t); p[0] = (f32x4){rs[0][0], rs[0][1], rs[0][2], rs[0][3]}; p[1] = (f32x4){rs[1][0], rs[1][1], rs[1][2], rs[1][3]}; }
;     DI void operator()(const AccT& acc, const Unit& u, const Unit& nxt, bool has_next, int wr, int wc, int fr, int fq, float (&rs_unused)[2][4]) const {
;     ...
;         if (has_next) {
; #pragma unroll
;             for (int ai = 0; ai < 2; ++ai)
; #pragma unroll
;                 for (int m = 0; m < 4; ++m) {
;                     float t = (nv[ai][m].x + nv[ai][m].y) + (nv[ai][m].z + nv[ai][m].w);
;                     t += __shfl_xor(t, 16); t += __shfl_xor(t, 32);
;                     rs[ai][m] = rsqrtf(t * (1.f / 1024.f) + EPS);
;                 }
;             park(rs, myt);
	s_waitcnt vmcnt(8)
	v_mov_b32_e32 v2, v154
	v_mov_b32_e32 v3, v155
	v_mov_b32_e32 v4, v156
	v_mov_b32_e32 v5, v157
	v_mov_b32_e32 v156, v158
	v_mov_b32_e32 v157, v98
	v_mov_b32_e32 v155, v100
	v_mov_b32_e32 v98, v159
	v_mov_b32_e32 v154, v160
	v_mov_b32_e32 v100, v161
	v_mov_b32_e32 v161, v118
	v_mov_b32_e32 v159, v120
	v_mov_b32_e32 v160, v162
	v_mov_b32_e32 v118, v163
	v_mov_b32_e32 v158, v164
	v_mov_b32_e32 v120, v165
	v_mov_b32_e32 v165, v138
	v_mov_b32_e32 v163, v140
	v_mov_b32_e32 v164, v166
	v_mov_b32_e32 v138, v167
	v_mov_b32_e32 v162, v168
	v_mov_b32_e32 v140, v169
	v_mov_b32_e32 v169, v142
	v_mov_b32_e32 v167, v144
	v_mov_b32_e32 v168, v2
	v_mov_b32_e32 v142, v3
	v_mov_b32_e32 v166, v4
	v_mov_b32_e32 v144, v5
	v_pk_add_f32 v[2:3], v[168:169], v[142:143]
	v_pk_add_f32 v[12:13], v[166:167], v[144:145]
	v_pk_add_f32 v[4:5], v[164:165], v[138:139]
	v_pk_add_f32 v[14:15], v[162:163], v[140:141]
	v_pk_add_f32 v[8:9], v[160:161], v[118:119]
	v_pk_add_f32 v[16:17], v[158:159], v[120:121]
	v_pk_add_f32 v[10:11], v[156:157], v[98:99]
	v_pk_add_f32 v[18:19], v[154:155], v[100:101]
	s_mov_b32 s0, 0x358637bd
	v_pk_add_f32 v[2:3], v[2:3], v[12:13]
	v_pk_add_f32 v[4:5], v[4:5], v[14:15]
	v_pk_add_f32 v[8:9], v[8:9], v[16:17]
	v_pk_add_f32 v[10:11], v[10:11], v[18:19]
	ds_bpermute_b32 v12, v174, v2
	ds_bpermute_b32 v13, v174, v3
	ds_bpermute_b32 v14, v174, v4
	ds_bpermute_b32 v15, v174, v5
	ds_bpermute_b32 v16, v174, v8
	ds_bpermute_b32 v17, v174, v9
	ds_bpermute_b32 v18, v174, v10
	ds_bpermute_b32 v19, v174, v11
	v_mov_b64_e32 v[6:7], s[0:1]
	s_waitcnt lgkmcnt(6)
	v_pk_add_f32 v[2:3], v[2:3], v[12:13]
	s_waitcnt lgkmcnt(4)
	v_pk_add_f32 v[4:5], v[4:5], v[14:15]
	s_waitcnt lgkmcnt(2)
	v_pk_add_f32 v[8:9], v[8:9], v[16:17]
	s_waitcnt lgkmcnt(0)
	v_pk_add_f32 v[10:11], v[10:11], v[18:19]
	ds_bpermute_b32 v12, v175, v2
	ds_bpermute_b32 v13, v175, v3
	ds_bpermute_b32 v14, v175, v4
	ds_bpermute_b32 v15, v175, v5
	ds_bpermute_b32 v16, v175, v8
	ds_bpermute_b32 v17, v175, v9
	ds_bpermute_b32 v18, v175, v10
	ds_bpermute_b32 v19, v175, v11
	s_waitcnt lgkmcnt(6)
	v_pk_add_f32 v[2:3], v[2:3], v[12:13]
	s_waitcnt lgkmcnt(4)
	v_pk_add_f32 v[4:5], v[4:5], v[14:15]
	s_waitcnt lgkmcnt(2)
	v_pk_add_f32 v[8:9], v[8:9], v[16:17]
	s_waitcnt lgkmcnt(0)
	v_pk_add_f32 v[10:11], v[10:11], v[18:19]
	v_pk_fma_f32 v[2:3], v[2:3], s[88:89], v[6:7] op_sel_hi:[1,0,0]
	v_pk_fma_f32 v[4:5], v[4:5], s[88:89], v[6:7] op_sel_hi:[1,0,0]
	v_pk_fma_f32 v[8:9], v[8:9], s[88:89], v[6:7] op_sel_hi:[1,0,0]
	v_pk_fma_f32 v[10:11], v[10:11], s[88:89], v[6:7] op_sel_hi:[1,0,0]
	v_mul_f32_e32 v12, 0x4b800000, v2
	v_cmp_gt_f32_e64 s[2:3], s42, v2
	v_cmp_gt_f32_e32 vcc, s42, v3
	s_nop 0
	v_cndmask_b32_e64 v2, v2, v12, s[2:3]
	v_mul_f32_e32 v12, 0x4b800000, v3
	v_cndmask_b32_e32 v3, v3, v12, vcc
	v_rsq_f32_e32 v2, v2
	v_rsq_f32_e32 v3, v3
	s_nop 0
	v_pk_mul_f32 v[12:13], v[2:3], s[52:53] op_sel_hi:[1,0]
	s_nop 0
	v_cndmask_b32_e32 v3, v3, v13, vcc
	v_cndmask_b32_e64 v2, v2, v12, s[2:3]
	v_mul_f32_e32 v14, 0x4b800000, v4
	v_cmp_gt_f32_e64 s[2:3], s42, v4
	v_cmp_gt_f32_e32 vcc, s42, v5
	s_nop 0
	v_cndmask_b32_e64 v4, v4, v14, s[2:3]
	v_mul_f32_e32 v14, 0x4b800000, v5
	v_cndmask_b32_e32 v5, v5, v14, vcc
	v_rsq_f32_e32 v4, v4
	v_rsq_f32_e32 v5, v5
	s_nop 0
	v_pk_mul_f32 v[14:15], v[4:5], s[52:53] op_sel_hi:[1,0]
	s_nop 0
	v_cndmask_b32_e32 v5, v5, v15, vcc
	v_cndmask_b32_e64 v4, v4, v14, s[2:3]
	v_mul_f32_e32 v16, 0x4b800000, v8
	v_cmp_gt_f32_e64 s[2:3], s42, v8
	v_cmp_gt_f32_e32 vcc, s42, v9
	s_nop 0
	v_cndmask_b32_e64 v8, v8, v16, s[2:3]
	v_mul_f32_e32 v16, 0x4b800000, v9
	v_cndmask_b32_e32 v9, v9, v16, vcc
	v_rsq_f32_e32 v8, v8
	v_rsq_f32_e32 v9, v9
	s_nop 0
	v_pk_mul_f32 v[16:17], v[8:9], s[52:53] op_sel_hi:[1,0]
	s_nop 0
	v_cndmask_b32_e32 v9, v9, v17, vcc
	v_cndmask_b32_e64 v8, v8, v16, s[2:3]
	v_mul_f32_e32 v18, 0x4b800000, v10
	v_cmp_gt_f32_e64 s[2:3], s42, v10
	v_cmp_gt_f32_e32 vcc, s42, v11
	s_nop 0
	v_cndmask_b32_e64 v10, v10, v18, s[2:3]
	v_mul_f32_e32 v18, 0x4b800000, v11
	v_cndmask_b32_e32 v11, v11, v18, vcc
	v_rsq_f32_e32 v10, v10
	v_rsq_f32_e32 v11, v11
	s_nop 0
	v_pk_mul_f32 v[18:19], v[10:11], s[52:53] op_sel_hi:[1,0]
	s_nop 0
	v_cndmask_b32_e32 v11, v11, v19, vcc
	v_cndmask_b32_e64 v10, v10, v18, s[2:3]
	s_andn2_b64 vcc, exec, s[6:7]
	ds_write_b128 v177, v[2:5]
	ds_write_b128 v177, v[8:11] offset:16
	s_cbranch_vccnz .LBB0_1812
	s_barrier
	s_branch .LBB0_1812

; DI unsigned xb_add(unsigned* p, unsigned v) { return __hip_atomic_fetch_add(p, v, __ATOMIC_RELAXED, __HIP_MEMORY_SCOPE_AGENT); }
; DI void xcd_barrier(int wv, unsigned* bar, volatile LAS unsigned* st) {
;     ...
;             __builtin_amdgcn_fence(__ATOMIC_ACQUIRE, "agent");
;             xb_add(&bar[XB_XGEN(x)], 1u);
;             asm volatile("s_waitcnt vmcnt(0)" ::: "memory");
.LBB0_1870:
	s_or_b64 exec, exec, s[2:3]
	v_mov_b32_e32 v0, s1
	v_add_co_u32_e32 v2, vcc, 0x2000, v0
	v_mov_b32_e32 v0, s0
	s_nop 0
	v_addc_co_u32_e32 v3, vcc, 0, v0, vcc
	v_mov_b32_e32 v0, 1
	s_waitcnt vmcnt(0) lgkmcnt(0)
	flat_atomic_add v[2:3], v0 offset:1024
	buffer_inv sc1
	s_waitcnt vmcnt(0)

; DI unsigned xb_add(unsigned* p, unsigned v) { return __hip_atomic_fetch_add(p, v, __ATOMIC_RELAXED, __HIP_MEMORY_SCOPE_AGENT); }
; DI void xcd_barrier(int wv, unsigned* bar, volatile LAS unsigned* st) {
;     ...
;             __builtin_amdgcn_fence(__ATOMIC_ACQUIRE, "agent");
;             xb_add(&bar[XB_XGEN(x)], 1u);
;             asm volatile("s_waitcnt vmcnt(0)" ::: "memory");
.LBB0_2136:
	s_or_b64 exec, exec, s[2:3]
	v_mov_b32_e32 v0, s26
	v_add_co_u32_e32 v2, vcc, 0x2000, v0
	v_mov_b32_e32 v0, s1
	s_nop 0
	v_addc_co_u32_e32 v3, vcc, 0, v0, vcc
	v_mov_b32_e32 v0, 1
	s_waitcnt vmcnt(0) lgkmcnt(0)
	flat_atomic_add v[2:3], v0 offset:1024
	buffer_inv sc1
	s_waitcnt vmcnt(0)

; DI unsigned xb_add(unsigned* p, unsigned v) { return __hip_atomic_fetch_add(p, v, __ATOMIC_RELAXED, __HIP_MEMORY_SCOPE_AGENT); }
; DI void xcd_barrier(int wv, unsigned* bar, volatile LAS unsigned* st) {
;     ...
;             __builtin_amdgcn_fence(__ATOMIC_ACQUIRE, "agent");
;             xb_add(&bar[XB_XGEN(x)], 1u);
;             asm volatile("s_waitcnt vmcnt(0)" ::: "memory");
.LBB0_2228:
	s_or_b64 exec, exec, s[4:5]
	v_mov_b32_e32 v0, s28
	v_add_co_u32_e32 v2, vcc, 0x2000, v0
	v_mov_b32_e32 v0, s1
	s_nop 0
	v_addc_co_u32_e32 v3, vcc, 0, v0, vcc
	v_mov_b32_e32 v0, 1
	s_waitcnt vmcnt(0) lgkmcnt(0)
	flat_atomic_add v[2:3], v0 offset:1024
	buffer_inv sc1
	s_waitcnt vmcnt(0)

; DI unsigned xb_add(unsigned* p, unsigned v) { return __hip_atomic_fetch_add(p, v, __ATOMIC_RELAXED, __HIP_MEMORY_SCOPE_AGENT); }
; DI void xcd_barrier(int wv, unsigned* bar, volatile LAS unsigned* st) {
;     ...
;             __builtin_amdgcn_fence(__ATOMIC_ACQUIRE, "agent");
;             xb_add(&bar[XB_XGEN(x)], 1u);
;             asm volatile("s_waitcnt vmcnt(0)" ::: "memory");
.LBB0_3065:
	s_or_b64 exec, exec, s[0:1]
	v_mov_b32_e32 v0, s23
	v_add_co_u32_e32 v0, vcc, 0x2000, v0
	v_mov_b32_e32 v1, s22
	s_nop 0
	v_addc_co_u32_e32 v1, vcc, 0, v1, vcc
	v_mov_b32_e32 v2, 1
	s_waitcnt vmcnt(0) lgkmcnt(0)
	flat_atomic_add v[0:1], v2 offset:1024
	buffer_inv sc1
	s_waitcnt vmcnt(0)
